# scan chunk bookkeeping incremental + 32 B never-executed padding so the code after the scan keeps the previous version's byte phase
# baseline (speedup 1.0000x reference)
; #define LAS __attribute__((address_space(3)))
; __device__ __forceinline__ void rwkv_scan_unit(LAS unsigned char* lds, const float* Wd, const float* V, const bf16_t* RKKB, float* Yraw, int p, int rg, int tid) {
;     const int lane = tid & 63, wave = __builtin_amdgcn_readfirstlane(tid >> 6);
;     constexpr int NCH = SEQ / SCAN_CH;
;     scan_load_chunk(lds + (tid >> 8) * SCAN_SLOT_B, Wd, V, RKKB, p, rg, (tid >> 8) * SCAN_CH, tid & 255);
;     __syncthreads();
;     f32x4 S = (f32x4){0.f, 0.f, 0.f, 0.f};
;     const int kq = lane & 15, rl = wave * 4 + (lane >> 4);
;     for (int c = 0; c < NCH; ++c) {
;         if (wave >= 4) { if (c + 2 < NCH) scan_load_chunk(lds + ((c + 2) % 3) * SCAN_SLOT_B, Wd, V, RKKB, p, rg, (c + 2) * SCAN_CH, tid - 256); }
;         else {
;             LAS const unsigned char* sl = lds + (c % 3) * SCAN_SLOT_B + kq * 16;
;             LAS const unsigned char* vl = lds + (c % 3) * SCAN_SLOT_B + 1280 + rl * 4;
;             float* yo = Yraw + ((size_t)p * SEQ + c * SCAN_CH + kq) * 64 + rg * 16 + rl;
;             f32x4 w = *(LAS const f32x4*)(sl), b = *(LAS const f32x4*)(sl + 256), k = *(LAS const f32x4*)(sl + 512), kk = *(LAS const f32x4*)(sl + 768), r = *(LAS const f32x4*)(sl + 1024);
;             float v = *(LAS const float*)(vl); float yp[16];
.LBB0_340:
	s_or_b64 exec, exec, s[6:7]
	v_add3_u32 v14, v14, v10, v22
	s_waitcnt vmcnt(0)
	v_lshlrev_b32_e32 v10, 16, v2
	v_and_b32_e32 v11, 0xffff0000, v2
	v_lshlrev_b32_e32 v12, 16, v3
	v_and_b32_e32 v13, 0xffff0000, v3
	v_lshlrev_b32_e32 v2, 16, v4
	v_and_b32_e32 v3, 0xffff0000, v4
	v_lshlrev_b32_e32 v4, 16, v5
	v_and_b32_e32 v5, 0xffff0000, v5
	ds_write_b128 v14, v[10:13] offset:10752
	ds_write_b128 v14, v[2:5] offset:10768
	s_and_saveexec_b64 s[6:7], s[4:5]
	v_lshrrev_b32_e32 v2, 8, v232
	v_lshlrev_b32_e32 v2, 11, v2
	v_and_b32_e32 v3, 3, v232
	v_lshl_or_b32 v2, v3, 9, v2
	v_and_b32_e32 v3, 0xfc, v232
	v_or_b32_e32 v2, v2, v3
	v_add_u32_e32 v2, 0x1f800, v2
	ds_write_b32 v2, v6
	ds_write_b32 v2, v7 offset:128
	ds_write_b32 v2, v8 offset:256
	ds_write_b32 v2, v9 offset:384
	s_or_b64 exec, exec, s[6:7]
	v_and_b32_e32 v3, 4, v32
	v_cmp_eq_u32_e64 s[6:7], 0, v3
	v_and_b32_e32 v3, 1, v32
	s_ashr_i32 s4, s10, 6
	v_and_b32_e32 v4, 2, v32
	v_cmp_eq_u32_e64 s[10:11], 0, v3
	v_add_u32_e32 v3, 0xffffff00, v32
	v_add_u32_e32 v12, 0x100, v32
	v_add_u32_e32 v14, 0x200, v32
	s_cmp_lt_i32 s4, 4
	v_cmp_eq_u32_e64 s[8:9], 0, v4
	v_ashrrev_i32_e32 v4, 4, v3
	v_ashrrev_i32_e32 v6, 4, v32
	v_ashrrev_i32_e32 v8, 5, v3
	v_ashrrev_i32_e32 v10, 5, v32
	v_ashrrev_i32_e32 v12, 5, v12
	v_ashrrev_i32_e32 v14, 5, v14
	v_ashrrev_i32_e32 v16, 2, v3
	s_movk_i32 s19, 0x540
	s_cselect_b64 s[16:17], -1, 0
	v_mul_lo_u32 v74, v4, s19
	v_mul_lo_u32 v75, v6, s19
	v_mul_lo_u32 v77, v8, s19
	v_mul_lo_u32 v78, v10, s19
	v_mul_lo_u32 v79, v12, s19
	v_mul_lo_u32 v80, v14, s19
	v_mul_lo_u32 v81, v16, s19
	s_and_b32 s23, s20, 7
	s_ashr_i32 s19, s18, 31
	s_lshl_b32 s21, s23, 22
	s_lshl_b64 s[24:25], s[18:19], 20
	v_ashrrev_i32_e32 v17, 31, v16
	v_lshlrev_b32_e32 v19, 5, v32
	s_add_u32 s24, s21, s24
	v_and_b32_e32 v76, 0xe0, v19
	s_addc_u32 s25, 0, s25
	v_lshlrev_b64 v[16:17], 8, v[16:17]
	s_lshl_b32 s20, s20, 3
	v_and_b32_e32 v19, 3, v3
	v_lshl_add_u64 v[16:17], s[24:25], 0, v[16:17]
	s_and_b32 s26, s20, 0xc0
	v_lshlrev_b32_e32 v19, 4, v19
	v_readlane_b32 s20, v254, 47
	v_or3_b32 v16, v16, s26, v19
	v_readlane_b32 s21, v254, 48
	s_lshl_b32 s27, s23, 23
	v_ashrrev_i32_e32 v5, 31, v4
	v_lshl_add_u64 v[46:47], s[20:21], 0, v[16:17]
	s_lshl_b64 s[20:21], s[18:19], 21
	v_ashrrev_i32_e32 v7, 31, v6
	v_ashrrev_i32_e32 v9, 31, v8
	v_ashrrev_i32_e32 v11, 31, v10
	v_ashrrev_i32_e32 v13, 31, v12
	v_ashrrev_i32_e32 v15, 31, v14
	s_add_u32 s20, s27, s20
	v_lshlrev_b32_e32 v18, 4, v3
	s_addc_u32 s21, 0, s21
	v_lshlrev_b64 v[14:15], 9, v[14:15]
	v_lshlrev_b64 v[12:13], 9, v[12:13]
	v_lshlrev_b64 v[10:11], 9, v[10:11]
	v_lshlrev_b64 v[8:9], 9, v[8:9]
	v_lshlrev_b64 v[6:7], 8, v[6:7]
	v_lshlrev_b64 v[4:5], 8, v[4:5]
	v_and_b32_e32 v73, 0xf0, v18
	v_lshl_add_u64 v[14:15], s[20:21], 0, v[14:15]
	v_lshl_add_u64 v[12:13], s[20:21], 0, v[12:13]
	v_lshl_add_u64 v[10:11], s[20:21], 0, v[10:11]
	v_lshl_add_u64 v[8:9], s[20:21], 0, v[8:9]
	v_lshl_add_u64 v[6:7], s[24:25], 0, v[6:7]
	v_readlane_b32 s20, v254, 51
	v_lshl_add_u64 v[4:5], s[24:25], 0, v[4:5]
	v_or_b32_e32 v6, v6, v73
	v_readlane_b32 s21, v254, 52
	v_or_b32_e32 v4, v4, v73
	s_lshl_b64 s[18:19], s[18:19], 12
	v_lshl_add_u64 v[56:57], s[20:21], 0, v[6:7]
	v_lshl_add_u64 v[58:59], s[20:21], 0, v[4:5]
	s_lshl_b32 s20, s23, 14
	s_add_u32 s18, s20, s18
	v_and_b32_e32 v0, 15, v32
	s_addc_u32 s19, 0, s19
	v_bfe_u32 v2, v32, 4, 2
	v_and_b32_e32 v3, 7, v3
	v_or_b32_e32 v4, s18, v0
	v_mov_b32_e32 v5, s19
	v_lshl_or_b32 v2, s4, 2, v2
	v_and_b32_e32 v16, 0x180, v18
	v_lshlrev_b32_e32 v3, 4, v3
	v_lshlrev_b64 v[4:5], 8, v[4:5]
	v_or3_b32 v14, v14, v16, v3
	v_or3_b32 v12, v12, v16, v3
	v_or3_b32 v10, v10, v16, v3
	v_or3_b32 v8, v8, v16, v3
	v_or_b32_e32 v4, s26, v4
	v_ashrrev_i32_e32 v3, 31, v2
	v_lshlrev_b32_e32 v72, 2, v2
	v_lshl_add_u64 v[2:3], v[2:3], 2, v[4:5]
	v_readlane_b32 s28, v254, 49
	v_lshl_add_u64 v[60:61], s[92:93], 0, v[2:3]
	v_mov_b32_e32 v2, v1
	v_mov_b32_e32 v3, v1
	v_lshlrev_b32_e32 v71, 4, v0
	v_cmp_gt_u32_e64 s[4:5], 8, v0
	s_movk_i32 s12, 0x180
	v_readlane_b32 s29, v254, 50
	v_mov_b32_e32 v0, v1
	v_mov_b64_e32 v[4:5], v[2:3]
	s_mov_b32 s22, 0
	v_cmp_gt_i32_e64 s[12:13], s12, v32
	v_and_b32_e32 v82, 48, v18
	v_lshl_add_u64 v[48:49], s[28:29], 0, v[14:15]
	v_lshl_add_u64 v[50:51], s[28:29], 0, v[12:13]
	v_lshl_add_u64 v[52:53], s[28:29], 0, v[10:11]
	v_lshl_add_u64 v[54:55], s[28:29], 0, v[8:9]
	v_mov_b64_e32 v[2:3], v[0:1]
	s_waitcnt lgkmcnt(0)
	s_barrier
	s_and_b64 vcc, exec, s[16:17]
	s_cbranch_vccz .Lscan_ldprime
	s_setprio 3
	v_lshlrev_b32_e32 v96, 5, v72
	v_add_u32_e32 v96, 0x1f800, v96
	ds_read_b128 v[116:119], v96
	ds_read_b128 v[132:135], v71 offset:768
	ds_read_b128 v[120:123], v71
	ds_read_b128 v[128:131], v71 offset:512
	ds_read_b128 v[124:127], v71 offset:256
	ds_read_b128 v[136:139], v71 offset:1024
	ds_read_b128 v[156:159], v71 offset:2112
	ds_read_b128 v[144:147], v71 offset:1344
	ds_read_b128 v[152:155], v71 offset:1856
	ds_read_b128 v[148:151], v71 offset:1600
	ds_read_b128 v[160:163], v71 offset:2368
	s_mov_b32 s18, 0
	s_mov_b32 s19, 0xa800
	v_lshl_add_u64 v[62:63], v[60:61], 0, s[14:15]
	s_mov_b64 s[20:21], 0x16100000
	v_lshl_add_u64 v[88:89], v[62:63], 0, s[20:21]
	s_mov_b64 s[20:21], 0x16101000
	v_lshl_add_u64 v[90:91], v[62:63], 0, s[20:21]
	s_branch .Lscan_top
	s_nop 0
	s_nop 0
	s_nop 0
	s_nop 0
	s_nop 0
	s_nop 0
	s_nop 0
	s_nop 0
